# global attention steady loop: row sums by f32 VALU adds instead of 4 all-ones MFMAs per tile
# speedup vs baseline: 1.1999x; 1.1999x over previous
; DI void attn_item(const Params& p, int layer, int item, char* smem) {
;   const int tid = tidx(), lane = tid & 63, wid = tid >> 6, l32 = lane & 31, h = lane >> 5;
;   int mode, b, hh, qb;
;   if (item < NAT_C) { mode = 0; b = item / 96; int rem = item % 96; hh = rem >> 4; qb = rem & 15; }
;   else if (item < NAT_C + NAT_B) { int it = item - NAT_C; mode = 1; b = it >> 6; hh = (it & 63) >> 4; qb = it & 15; }
;   else if (item < NAT_LAT) { int it = item - NAT_C - NAT_B; mode = 2; b = it / 96; int rem = it % 96; hh = rem >> 4; qb = rem & 15; }
;   else { int it = item - NAT_LAT; mode = 3; b = it >> 4; hh = it & 15; qb = 0; }
;   int qchunk, kchunk, vchunk, head16, t0 = 0, t1 = 0, qpos0 = qb * 256;
;   bool hasSink = false; float sinkv = 0.f;
;   int maskmode = 0;
;   if (mode == 0) { qchunk = 22 + hh; kchunk = 28 + hh / 3; vchunk = 30 + hh / 3; head16 = 10 + hh; t0 = 0; t1 = 64; }
;   else if (mode == 1) {
;     qchunk = 10 + hh; kchunk = 14 + hh; vchunk = 18 + hh; head16 = 6 + hh; maskmode = 1;
;     t0 = min(max(4 * qb - 4, 0), 56); t1 = min(max(4 * qb + 3 - 4, 0), 56) + 8;
;   } else if (mode == 2) {
;     qchunk = hh; kchunk = 6 + hh / 3; vchunk = 8 + hh / 3; head16 = hh; maskmode = 2;
;     t0 = max(0, 4 * qb - 2); t1 = min(64, 4 * qb + 6); hasSink = true; sinkv = p.sink[layer * 6 + hh];
;   } else {
;     head16 = hh; qpos0 = 4096;
;     if (hh < 6) { qchunk = hh; kchunk = 6 + hh / 3; vchunk = 8 + hh / 3; hasSink = true; sinkv = p.sink[layer * 6 + hh]; }
;     else if (hh < 10) { int hb = hh - 6; qchunk = 10 + hb; kchunk = 14 + hb; vchunk = 18 + hb; }
;     else { int hc = hh - 10; qchunk = 22 + hc; kchunk = 28 + hc / 3; vchunk = 30 + hc / 3; }
;   }
;   const int n_it = 4 + (t1 - t0);
;   const u16* Qb = p.QKV + (size_t)(b * 32 + qchunk) * LTOT * 64;
;   const u16* Kb = p.QKV + (size_t)(b * 32 + kchunk) * LTOT * 64;
;   const u16* Vb = p.QKV + (size_t)(b * 32 + vchunk) * LTOT * 64;
;   float* s_rpb = (float*)(smem + RPB_OFF);
;   if (mode == 1) {
;     const float* rp = p.rpb + (size_t)(layer * 4 + hh) * 465;
;     for (int e = tid; e < 465; e += NTHR) s_rpb[e] = rp[e] * LOG2E;
;   }
;   const int qpos = qpos0 + wid * 32 + l32;
;   bf16x8 qf[4];
; #pragma unroll
;   for (int s = 0; s < 4; ++s) qf[s] = *(const bf16x8*)(Qb + (size_t)qpos * 64 + s * 16 + h * 8);
;   f32x16 o0, o1;
; #pragma unroll
.LBB0_259:
	s_mul_hi_i32 s0, s14, 0x2aaaaaab
	s_lshr_b32 s1, s0, 31
	s_ashr_i32 s5, s0, 4
	s_add_i32 s5, s5, s1
	s_mul_i32 s0, s5, 0x60
	s_sub_i32 s0, s14, s0
	v_mov_b32_e32 v32, v213
	s_ashr_i32 s4, s0, 4
	s_lshl_b32 s0, s0, 8
	s_and_b32 s8, s0, 0xf00
	s_lshl_b32 s0, s5, 5
	v_ashrrev_i32_e32 v0, 1, v32
	s_add_i32 s1, s4, s0
	s_mul_i32 s2, s4, 0x56
	v_and_b32_e32 v0, 0xffffffe0, v0
	v_and_b32_e32 v36, 31, v32
	s_bfe_u32 s3, s2, 0x1000f
	s_bfe_u32 s2, s2, 0x80008
	s_add_i32 s1, s1, 22
	v_add_u32_e32 v0, s8, v0
	s_add_i32 s2, s2, s3
	s_mul_hi_i32 s3, s1, 0x88000
	s_mul_i32 s1, s1, 0x88000
	v_or_b32_e32 v134, v0, v36
	s_add_u32 s6, s88, s1
	v_ashrrev_i32_e32 v135, 31, v134
	v_bfe_u32 v140, v32, 5, 1
	s_addc_u32 s7, s89, s3
	v_lshlrev_b64 v[2:3], 7, v[134:135]
	v_lshl_add_u64 v[2:3], s[6:7], 0, v[2:3]
	v_lshlrev_b32_e32 v18, 4, v140
	v_mov_b32_e32 v19, v1
	v_readlane_b32 s6, v254, 50
	v_lshl_add_u64 v[2:3], v[2:3], 0, v[18:19]
	v_readlane_b32 s7, v254, 51
	global_load_dwordx4 v[98:101], v[2:3], off
	global_load_dwordx4 v[102:105], v[2:3], off offset:32
	global_load_dwordx4 v[106:109], v[2:3], off offset:64
	global_load_dwordx4 v[110:113], v[2:3], off offset:96
	s_sext_i32_i8 s2, s2
	global_load_dword v0, v1, s[6:7] offset:8
	s_add_i32 s2, s0, s2
	s_mul_i32 s3, s2, 0x88000
	s_add_i32 s0, s2, 28
	s_mul_hi_i32 s1, s0, 0x88000
	s_add_i32 s0, s3, 0xee0000
	v_ashrrev_i32_e32 v30, 3, v32
	s_add_u32 s0, s88, s0
	v_ashrrev_i32_e32 v31, 31, v30
	s_addc_u32 s1, s89, s1
	v_lshlrev_b32_e32 v19, 4, v32
	v_lshlrev_b64 v[20:21], 7, v[30:31]
	v_lshl_add_u64 v[136:137], s[0:1], 0, v[20:21]
	s_mov_b32 s6, 0x80000
	s_add_i32 s2, s2, 30
	s_add_i32 s3, s3, 0xff0000
	s_mul_hi_i32 s9, s2, 0x88000
	s_add_u32 s2, s88, s3
	s_addc_u32 s3, s89, s9
	v_mov_b64_e32 v[26:27], s[2:3]
	v_mad_i64_i32 v[138:139], s[2:3], v30, s28, v[26:27]
	s_movk_i32 s3, 0x90
	s_mov_b32 s2, 0x82000
	v_mul_lo_u32 v30, v30, s3
	v_add_u32_e32 v30, 16, v30
	v_add_u32_e32 v144, 16, v18
	v_mul_u32_u24_e32 v145, 0x90, v36
	v_mad_u32_u24 v146, v36, s3, v144
	s_waitcnt vmcnt(0)
	v_xor_b32_e32 v2, 0x80000000, v0
	v_and_b32_e32 v0, 0x70, v19
	v_lshl_add_u64 v[34:35], v[136:137], 0, v[0:1]
	v_add_co_u32_e32 v22, vcc, s6, v34
	v_add_u32_e32 v135, v30, v0
	s_nop 0
	v_addc_co_u32_e32 v23, vcc, 0, v35, vcc
	global_load_dwordx4 v[22:25], v[22:23], off
	v_add_co_u32_e32 v26, vcc, s2, v34
	v_lshl_add_u64 v[74:75], v[138:139], 0, v[0:1]
	s_nop 0
	v_addc_co_u32_e32 v27, vcc, 0, v35, vcc
	global_load_dwordx4 v[26:29], v[26:27], off
	s_movk_i32 s2, 0x2000
	v_mov_b32_e32 v3, v2
	v_mov_b32_e32 v4, v2
	v_mov_b32_e32 v5, v2
	v_mov_b32_e32 v6, v2
	v_mov_b32_e32 v7, v2
	v_mov_b32_e32 v8, v2
	v_mov_b32_e32 v9, v2
	v_mov_b32_e32 v10, v2
	v_mov_b32_e32 v11, v2
	v_mov_b32_e32 v12, v2
	v_mov_b32_e32 v13, v2
	v_mov_b32_e32 v14, v2
	v_mov_b32_e32 v15, v2
	v_mov_b32_e32 v16, v2
	v_mov_b32_e32 v17, v2
	s_waitcnt vmcnt(0)
	ds_write_b128 v135, v[22:25]
	v_lshlrev_b32_e32 v22, 3, v32
	v_and_b32_e32 v22, 8, v22
	v_and_or_b32 v19, v19, s74, v22
	v_add_co_u32_e32 v22, vcc, s2, v74
	v_add_u32_e32 v19, v30, v19
	s_nop 0
	v_addc_co_u32_e32 v23, vcc, 0, v75, vcc
	global_load_dwordx4 v[30:33], v[22:23], off
	s_mov_b32 s2, 0x84000
	v_add_co_u32_e32 v24, vcc, s2, v34
	v_add_u32_e32 v141, 0x2000, v19
	s_nop 0
	v_addc_co_u32_e32 v25, vcc, 0, v35, vcc
	global_load_dwordx4 v[66:69], v[24:25], off
	v_lshl_add_u64 v[24:25], s[0:1], 0, v[0:1]
	v_lshl_add_u64 v[76:77], v[24:25], 0, v[20:21]
	s_mov_b32 s0, 0x86000
	v_add_u32_e32 v143, 0x6800, v19
	s_waitcnt vmcnt(0)
	ds_write2_b64 v141, v[30:31], v[32:33] offset0:128 offset1:130
	v_mad_u32_u24 v30, v36, s3, 16
	v_add_u32_e32 v142, v30, v18
	global_load_dwordx4 v[70:73], v[22:23], off offset:256
	global_load_dwordx4 v[30:33], v[22:23], off offset:128
	v_add_co_u32_e32 v18, vcc, s0, v76
	s_waitcnt lgkmcnt(0)
	s_barrier
	ds_write_b128 v135, v[26:29] offset:18432
	v_addc_co_u32_e32 v19, vcc, 0, v77, vcc
	s_waitcnt vmcnt(0)
	ds_write2_b64 v143, v[30:31], v[32:33] offset0:128 offset1:130
	global_load_dwordx4 v[114:117], v[18:19], off
	global_load_dwordx4 v[118:121], v[22:23], off offset:384
	ds_read_b128 v[34:37], v146
	ds_read_b128 v[38:41], v146 offset:32
	v_mov_b64_e32 v[132:133], s[94:95]
	v_mov_b64_e32 v[130:131], s[92:93]
	s_waitcnt lgkmcnt(1)
	v_mfma_f32_32x32x16_bf16 v[18:33], v[34:37], v[98:101], v[2:17]
	ds_read_b128 v[34:37], v146 offset:64
	ds_read_b128 v[50:53], v146 offset:4608
	s_waitcnt lgkmcnt(2)
	v_mfma_f32_32x32x16_bf16 v[18:33], v[38:41], v[102:105], v[18:33]
	s_waitcnt lgkmcnt(1)
	v_mfma_f32_32x32x16_bf16 v[18:33], v[34:37], v[106:109], v[18:33]
	ds_read_b128 v[34:37], v146 offset:96
	s_waitcnt lgkmcnt(0)
	v_mfma_f32_32x32x16_bf16 v[18:33], v[34:37], v[110:113], v[18:33]
	v_mfma_f32_32x32x16_bf16 v[34:49], v[50:53], v[98:101], v[2:17]
	ds_read_b128 v[50:53], v146 offset:4640
	s_nop 9
	v_exp_f32_e32 v18, v18
	v_exp_f32_e32 v19, v19
	v_exp_f32_e32 v20, v20
	v_exp_f32_e32 v21, v21
	v_exp_f32_e32 v22, v22
	v_exp_f32_e32 v23, v23
	s_waitcnt lgkmcnt(0)
	v_mfma_f32_32x32x16_bf16 v[34:49], v[50:53], v[102:105], v[34:49]
	ds_read_b128 v[50:53], v146 offset:4672
	v_exp_f32_e32 v24, v24
	v_exp_f32_e32 v25, v25
	v_cvt_pk_bf16_f32 v18, v18, v19
	v_cvt_pk_bf16_f32 v19, v20, v21
	v_cvt_pk_bf16_f32 v20, v22, v23
	v_cvt_pk_bf16_f32 v21, v24, v25
	s_waitcnt lgkmcnt(0)
	v_mfma_f32_32x32x16_bf16 v[34:49], v[50:53], v[106:109], v[34:49]
	ds_read_b128 v[50:53], v146 offset:4704
	ds_read_b128 v[22:25], v142 offset:9216
	ds_read_b128 v[78:81], v142 offset:9248
	v_exp_f32_e32 v82, v26
	v_exp_f32_e32 v83, v27
	v_exp_f32_e32 v84, v28
	v_exp_f32_e32 v85, v29
	v_exp_f32_e32 v122, v30
	s_waitcnt lgkmcnt(2)
; #define MFMA32(a, b, c) __builtin_amdgcn_mfma_f32_32x32x16_bf16((a), (b), (c), 0, 0, 0)
; DI void attn_item(const Params& p, int layer, int item, char* smem) {
;     ...
; #pragma unroll
;       for (int r = 0; r < 16; ++r) {
;         S[0][r] = __builtin_amdgcn_exp2f(S[0][r]);
;         S[1][r] = __builtin_amdgcn_exp2f(S[1][r]);
;       }
; #pragma unroll
;       for (int kt = 0; kt < 2; ++kt)
; #pragma unroll
;         for (int s2 = 0; s2 < 2; ++s2) {
;           uint4 pw;
;           pw.x = pack_bf16(S[kt][8 * s2 + 0], S[kt][8 * s2 + 1]);
;           pw.y = pack_bf16(S[kt][8 * s2 + 2], S[kt][8 * s2 + 3]);
;           pw.z = pack_bf16(S[kt][8 * s2 + 4], S[kt][8 * s2 + 5]);
;           pw.w = pack_bf16(S[kt][8 * s2 + 6], S[kt][8 * s2 + 7]);
;           bf16x8 pf = __builtin_bit_cast(bf16x8, pw);
;           const int koff = (kt * 32 + 16 * s2 + 8 * h) * 2;
;           {
;             bf16x8 vf = *(const bf16x8*)(sV + l32 * VROW + koff);
;             o0 = MFMA32(vf, pf, o0);
;             lacc = MFMA32(ones, pf, lacc);
;           }
;           {
;             bf16x8 vf = *(const bf16x8*)(sV + (32 + l32) * VROW + koff);
;             o1 = MFMA32(vf, pf, o1);
;           }
;         }
;     ...
;   for (int it = 0; it < n_it; it += 2) {
;     if (it + 1 < n_it) { ASWRITE(kb0, vb0, 1); }
;     if (it + 3 < n_it) { AGLOAD(kb0, vb0, TILE_OF(it + 3)); }
;     __builtin_amdgcn_sched_barrier(0);
;     compute(0, TILE_OF(it));
;     __syncthreads();
;     if (it + 1 < n_it) {
;       if (it + 2 < n_it) { ASWRITE(ka0, va0, 0); }
;       if (it + 4 < n_it) { AGLOAD(ka0, va0, TILE_OF(it + 4)); }
;       __builtin_amdgcn_sched_barrier(0);
;       compute(1, TILE_OF(it + 1));
;       __syncthreads();
	v_mfma_f32_32x32x16_bf16 v[34:49], v[50:53], v[110:113], v[34:49]
	v_exp_f32_e32 v124, v31
	v_exp_f32_e32 v126, v32
	v_exp_f32_e32 v128, v33
	v_cvt_pk_bf16_f32 v82, v82, v83
	v_cvt_pk_bf16_f32 v83, v84, v85
	v_cvt_pk_bf16_f32 v84, v122, v124
	v_cvt_pk_bf16_f32 v85, v126, v128
	s_nop 4
	v_exp_f32_e32 v86, v34
	v_exp_f32_e32 v87, v35
	v_exp_f32_e32 v88, v36
	v_exp_f32_e32 v89, v37
	v_exp_f32_e32 v90, v38
	v_exp_f32_e32 v91, v39
	v_exp_f32_e32 v92, v40
	v_exp_f32_e32 v93, v41
	v_exp_f32_e32 v94, v42
	v_exp_f32_e32 v95, v43
	v_exp_f32_e32 v96, v44
	v_exp_f32_e32 v97, v45
	v_exp_f32_e32 v123, v46
	v_exp_f32_e32 v125, v47
	v_exp_f32_e32 v127, v48
	v_exp_f32_e32 v129, v49
	s_waitcnt lgkmcnt(1)
	v_mfma_f32_32x32x16_bf16 v[34:49], v[22:25], v[18:21], 0
	ds_read_b128 v[22:25], v142 offset:13824
	s_waitcnt lgkmcnt(1)
	v_mfma_f32_32x32x16_bf16 v[34:49], v[78:81], v[82:85], v[34:49]
	ds_read_b128 v[78:81], v142 offset:13856
	v_mfma_f32_32x32x16_bf16 v[50:65], v[130:133], v[18:21], 0
	s_waitcnt lgkmcnt(1)
	v_mfma_f32_32x32x16_bf16 v[18:33], v[22:25], v[18:21], 0
	v_mfma_f32_32x32x16_bf16 v[50:65], v[130:133], v[82:85], v[50:65]
	s_waitcnt lgkmcnt(0)
	v_mfma_f32_32x32x16_bf16 v[18:33], v[78:81], v[82:85], v[18:33]
	ds_read_b128 v[82:85], v142 offset:9280
	v_cvt_pk_bf16_f32 v78, v86, v87
	v_cvt_pk_bf16_f32 v79, v88, v89
	v_cvt_pk_bf16_f32 v80, v90, v91
	v_cvt_pk_bf16_f32 v81, v92, v93
	s_waitcnt lgkmcnt(0)
	s_nop 0
	v_mfma_f32_32x32x16_bf16 v[34:49], v[82:85], v[78:81], v[34:49]
	ds_read_b128 v[82:85], v142 offset:13888
	s_waitcnt lgkmcnt(0)
	v_mfma_f32_32x32x16_bf16 v[18:33], v[82:85], v[78:81], v[18:33]
	ds_read_b128 v[82:85], v142 offset:9312
	v_mfma_f32_32x32x16_bf16 v[50:65], v[130:133], v[78:81], v[50:65]
	v_cvt_pk_bf16_f32 v78, v94, v95
	v_cvt_pk_bf16_f32 v79, v96, v97
	v_cvt_pk_bf16_f32 v80, v123, v125
	v_cvt_pk_bf16_f32 v81, v127, v129
	s_waitcnt lgkmcnt(0)
	s_nop 0
	v_mfma_f32_32x32x16_bf16 v[34:49], v[82:85], v[78:81], v[34:49]
	ds_read_b128 v[82:85], v142 offset:13920
	s_waitcnt lgkmcnt(0)
	s_barrier
	ds_write_b128 v135, v[66:69]
	ds_write2_b64 v141, v[70:71], v[72:73] offset0:128 offset1:130
	global_load_dwordx4 v[122:125], v[76:77], off
	global_load_dwordx4 v[126:129], v[74:75], off
	v_mfma_f32_32x32x16_bf16 v[50:65], v[130:133], v[78:81], v[50:65]
	v_mfma_f32_32x32x16_bf16 v[18:33], v[82:85], v[78:81], v[18:33]
	ds_read_b128 v[82:85], v146 offset:18432
	ds_read_b128 v[86:89], v146 offset:18464
	s_mov_b32 s2, 2
	v_add_u32_e32 v144, v144, v145
	s_waitcnt lgkmcnt(1)
	v_mfma_f32_32x32x16_bf16 v[66:81], v[82:85], v[98:101], v[2:17]
	ds_read_b128 v[82:85], v146 offset:18496
	ds_read_b128 v[148:151], v146 offset:23040
	s_waitcnt lgkmcnt(2)
	v_mfma_f32_32x32x16_bf16 v[66:81], v[86:89], v[102:105], v[66:81]
	s_waitcnt lgkmcnt(1)
	v_mfma_f32_32x32x16_bf16 v[66:81], v[82:85], v[106:109], v[66:81]
	ds_read_b128 v[82:85], v146 offset:18528
	s_waitcnt lgkmcnt(0)
	v_mfma_f32_32x32x16_bf16 v[66:81], v[82:85], v[110:113], v[66:81]
	v_mfma_f32_32x32x16_bf16 v[82:97], v[148:151], v[98:101], v[2:17]
	ds_read_b128 v[148:151], v146 offset:23072
	s_nop 9
	v_exp_f32_e32 v66, v66
	v_exp_f32_e32 v67, v67
	v_exp_f32_e32 v68, v68
	v_exp_f32_e32 v69, v69
	v_exp_f32_e32 v70, v70
	v_exp_f32_e32 v71, v71
	s_waitcnt lgkmcnt(0)
	v_mfma_f32_32x32x16_bf16 v[82:97], v[148:151], v[102:105], v[82:97]
	ds_read_b128 v[148:151], v146 offset:23104
	v_exp_f32_e32 v72, v72
	v_exp_f32_e32 v73, v73
	v_cvt_pk_bf16_f32 v66, v66, v67
	v_cvt_pk_bf16_f32 v67, v68, v69
	v_cvt_pk_bf16_f32 v68, v70, v71
	v_cvt_pk_bf16_f32 v69, v72, v73
	s_waitcnt lgkmcnt(0)
	v_mfma_f32_32x32x16_bf16 v[82:97], v[148:151], v[106:109], v[82:97]
	ds_read_b128 v[146:149], v146 offset:23136
	v_exp_f32_e32 v78, v78
	v_exp_f32_e32 v79, v79
	v_exp_f32_e32 v80, v80
	v_exp_f32_e32 v81, v81
	s_waitcnt lgkmcnt(0)
	v_mfma_f32_32x32x16_bf16 v[82:97], v[146:149], v[110:113], v[82:97]
	v_exp_f32_e32 v146, v74
	v_exp_f32_e32 v147, v75
	v_exp_f32_e32 v148, v76
	v_exp_f32_e32 v149, v77
	ds_read_b128 v[70:73], v142 offset:27648
	ds_read_b128 v[74:77], v142 offset:27680
	s_nop 5
	v_exp_f32_e32 v82, v82
	s_waitcnt lgkmcnt(1)
	v_mfma_f32_32x32x16_bf16 v[34:49], v[70:73], v[66:69], v[34:49]
	ds_read_b128 v[70:73], v142 offset:32256
	v_exp_f32_e32 v83, v83
	v_exp_f32_e32 v84, v84
	v_exp_f32_e32 v85, v85
	v_exp_f32_e32 v86, v86
	v_exp_f32_e32 v87, v87
	v_exp_f32_e32 v88, v88
	s_waitcnt lgkmcnt(0)
	v_mfma_f32_32x32x16_bf16 v[18:33], v[70:73], v[66:69], v[18:33]
	ds_read_b128 v[70:73], v142 offset:32288
	v_exp_f32_e32 v89, v89
	v_exp_f32_e32 v90, v90
	v_exp_f32_e32 v91, v91
	v_exp_f32_e32 v92, v92
	v_exp_f32_e32 v93, v93
	v_exp_f32_e32 v94, v94
	v_mfma_f32_32x32x16_bf16 v[50:65], v[130:133], v[66:69], v[50:65]
	v_cvt_pk_bf16_f32 v66, v146, v147
	v_cvt_pk_bf16_f32 v67, v148, v149
	v_cvt_pk_bf16_f32 v68, v78, v79
	v_cvt_pk_bf16_f32 v69, v80, v81
	v_exp_f32_e32 v95, v95
	v_exp_f32_e32 v96, v96
	v_exp_f32_e32 v97, v97
	s_waitcnt lgkmcnt(0)
	v_mfma_f32_32x32x16_bf16 v[18:33], v[70:73], v[66:69], v[18:33]
	ds_read_b128 v[70:73], v142 offset:27712
	v_mfma_f32_32x32x16_bf16 v[34:49], v[74:77], v[66:69], v[34:49]
	v_mfma_f32_32x32x16_bf16 v[50:65], v[130:133], v[66:69], v[50:65]
	v_cvt_pk_bf16_f32 v66, v82, v83
	v_cvt_pk_bf16_f32 v67, v84, v85
	v_cvt_pk_bf16_f32 v68, v86, v87
	v_cvt_pk_bf16_f32 v69, v88, v89
	s_waitcnt lgkmcnt(0)
	s_nop 0
	v_mfma_f32_32x32x16_bf16 v[34:49], v[70:73], v[66:69], v[34:49]
	ds_read_b128 v[70:73], v142 offset:32320
	s_waitcnt lgkmcnt(0)
	v_mfma_f32_32x32x16_bf16 v[18:33], v[70:73], v[66:69], v[18:33]
	ds_read_b128 v[70:73], v142 offset:27744
	v_mfma_f32_32x32x16_bf16 v[50:65], v[130:133], v[66:69], v[50:65]
	v_cvt_pk_bf16_f32 v66, v90, v91
	v_cvt_pk_bf16_f32 v67, v92, v93
	v_cvt_pk_bf16_f32 v68, v94, v95
	v_cvt_pk_bf16_f32 v69, v96, v97
	s_waitcnt lgkmcnt(0)
	s_nop 0
	v_mfma_f32_32x32x16_bf16 v[34:49], v[70:73], v[66:69], v[34:49]
	ds_read_b128 v[70:73], v142 offset:32352
	s_waitcnt lgkmcnt(0)
	s_barrier
	v_mfma_f32_32x32x16_bf16 v[50:65], v[130:133], v[66:69], v[50:65]
	v_mfma_f32_32x32x16_bf16 v[18:33], v[70:73], v[66:69], v[18:33]
	s_nop 11
	v_mov_b32_e32 v51, 0
	v_mov_b32_e32 v52, 0
	s_branch .LBB0_261
; DI void attn_item(const Params& p, int layer, int item, char* smem) {
;     ...
;       f32x16 S[2];
; #pragma unroll
;       for (int kt = 0; kt < 2; ++kt) {
; #pragma unroll
;         for (int s = 0; s < 4; ++s) {
;           bf16x8 kf = *(const bf16x8*)(sK + (kt * 32 + l32) * KROW + s * 32 + h * 16);
;           S[kt] = MFMA32(kf, qf[s], s == 0 ? cinit : S[kt]);
;         }
;       }
;       if (tile < 64 && maskmode == 1) {
;         int qr = tq >> 6, qc = tq & 63;
;         int ws = min(max(qc - 8, 0), 48);
;         int dr = tile - qr + 7;
; #pragma unroll
;         for (int kt = 0; kt < 2; ++kt)
; #pragma unroll
;           for (int r = 0; r < 16; ++r) {
;             int kc = kt * 32 + crow(r, h);
;             bool ok = (unsigned)(kc - ws) < 16u;
;             int bi = ok ? (dr * 31 + kc - qc + 15) : 0;
;             float bv = s_rpb[bi];
;             S[kt][r] = ok ? (S[kt][r] + bv) : -INFINITY;
;           }
;       } else if (tile < 64 && maskmode == 2) {
; #pragma unroll
;         for (int kt = 0; kt < 2; ++kt)
; #pragma unroll
;           for (int r = 0; r < 16; ++r) {
;             int tk = tile * 64 + kt * 32 + crow(r, h);
;             int dd = tq - tk;
;             bool ok = (dd <= 128) && (dd >= -128);
;             S[kt][r] = ok ? S[kt][r] : -INFINITY;
;           }
;       }
; #pragma unroll
;       for (int r = 0; r < 16; ++r) {
;         S[0][r] = __builtin_amdgcn_exp2f(S[0][r]);
;         S[1][r] = __builtin_amdgcn_exp2f(S[1][r]);
;       }
; #pragma unroll
;       for (int kt = 0; kt < 2; ++kt)
; #pragma unroll
;         for (int s2 = 0; s2 < 2; ++s2) {
;           uint4 pw;
;           pw.x = pack_bf16(S[kt][8 * s2 + 0], S[kt][8 * s2 + 1]);
;           pw.y = pack_bf16(S[kt][8 * s2 + 2], S[kt][8 * s2 + 3]);
;           pw.z = pack_bf16(S[kt][8 * s2 + 4], S[kt][8 * s2 + 5]);
;           pw.w = pack_bf16(S[kt][8 * s2 + 6], S[kt][8 * s2 + 7]);
;           bf16x8 pf = __builtin_bit_cast(bf16x8, pw);
;           const int koff = (kt * 32 + 16 * s2 + 8 * h) * 2;
;           {
;             bf16x8 vf = *(const bf16x8*)(sV + l32 * VROW + koff);
;             o0 = MFMA32(vf, pf, o0);
;             lacc = MFMA32(ones, pf, lacc);
;           }
;           {
;             bf16x8 vf = *(const bf16x8*)(sV + (32 + l32) * VROW + koff);
;             o1 = MFMA32(vf, pf, o1);
;           }
;         }
.LBB0_260:
	ds_read_b128 v[82:85], v144 offset:18432
	ds_read_b128 v[86:89], v144 offset:18464
	s_mov_b64 s[6:7], 0x100
	s_add_i32 s2, s2, 2
	v_lshl_add_u64 v[138:139], v[138:139], 0, s[6:7]
	s_waitcnt lgkmcnt(1)
	v_mfma_f32_32x32x16_bf16 v[66:81], v[82:85], v[98:101], v[2:17]
	ds_read_b128 v[82:85], v144 offset:18496
	ds_read_b128 v[130:133], v144 offset:23040
	v_lshl_add_u64 v[136:137], v[136:137], 0, s[96:97]
	s_andn2_b64 vcc, exec, s[0:1]
	s_waitcnt lgkmcnt(2)
	v_mfma_f32_32x32x16_bf16 v[66:81], v[86:89], v[102:105], v[66:81]
	s_waitcnt lgkmcnt(1)
	v_mfma_f32_32x32x16_bf16 v[66:81], v[82:85], v[106:109], v[66:81]
	ds_read_b128 v[82:85], v144 offset:18528
	s_waitcnt lgkmcnt(0)
	v_mfma_f32_32x32x16_bf16 v[66:81], v[82:85], v[110:113], v[66:81]
	v_mfma_f32_32x32x16_bf16 v[82:97], v[130:133], v[98:101], v[2:17]
	ds_read_b128 v[130:133], v144 offset:23072
	s_nop 9
	v_exp_f32_e32 v66, v66
	v_exp_f32_e32 v67, v67
	v_exp_f32_e32 v68, v68
	v_exp_f32_e32 v69, v69
	v_exp_f32_e32 v70, v70
	v_exp_f32_e32 v71, v71
	s_waitcnt lgkmcnt(0)
	v_mfma_f32_32x32x16_bf16 v[82:97], v[130:133], v[102:105], v[82:97]
	ds_read_b128 v[130:133], v144 offset:23104
	v_exp_f32_e32 v72, v72
	v_exp_f32_e32 v73, v73
	v_add_f32_e32 v51, v51, v66
	v_add_f32_e32 v52, v52, v67
	v_add_f32_e32 v51, v51, v68
	v_add_f32_e32 v52, v52, v69
	v_cvt_pk_bf16_f32 v66, v66, v67
	v_cvt_pk_bf16_f32 v67, v68, v69
	s_waitcnt lgkmcnt(0)
	v_mfma_f32_32x32x16_bf16 v[82:97], v[130:133], v[106:109], v[82:97]
	ds_read_b128 v[130:133], v144 offset:23136
	v_add_f32_e32 v51, v51, v70
	v_add_f32_e32 v52, v52, v71
	v_cvt_pk_bf16_f32 v68, v70, v71
	v_add_f32_e32 v51, v51, v72
	v_add_f32_e32 v52, v52, v73
	v_cvt_pk_bf16_f32 v69, v72, v73
	v_exp_f32_e32 v145, v78
	v_exp_f32_e32 v146, v79
	s_waitcnt lgkmcnt(0)
	v_mfma_f32_32x32x16_bf16 v[82:97], v[130:133], v[110:113], v[82:97]
	v_exp_f32_e32 v147, v80
	v_exp_f32_e32 v148, v81
	v_exp_f32_e32 v130, v74
	v_exp_f32_e32 v131, v75
	v_exp_f32_e32 v132, v76
	v_exp_f32_e32 v133, v77
	ds_read_b128 v[70:73], v142 offset:27648
	ds_read_b128 v[74:77], v142 offset:27680
	ds_read_b128 v[78:81], v142 offset:32256
	v_add_f32_e32 v51, v51, v145
	v_add_f32_e32 v52, v52, v146
	v_add_f32_e32 v51, v51, v147
	v_add_f32_e32 v52, v52, v148
	v_exp_f32_e32 v82, v82
	s_waitcnt lgkmcnt(2)
	v_mfma_f32_32x32x16_bf16 v[34:49], v[70:73], v[66:69], v[34:49]
	v_exp_f32_e32 v83, v83
	v_exp_f32_e32 v84, v84
	v_exp_f32_e32 v85, v85
	v_add_f32_e32 v51, v51, v130
	v_add_f32_e32 v52, v52, v131
	v_add_f32_e32 v51, v51, v132
	v_add_f32_e32 v52, v52, v133
	v_exp_f32_e32 v86, v86
	v_exp_f32_e32 v87, v87
	v_exp_f32_e32 v88, v88
	v_exp_f32_e32 v89, v89
	s_waitcnt lgkmcnt(0)
	v_mfma_f32_32x32x16_bf16 v[18:33], v[78:81], v[66:69], v[18:33]
	v_cvt_pk_bf16_f32 v66, v130, v131
	v_cvt_pk_bf16_f32 v67, v132, v133
	v_cvt_pk_bf16_f32 v68, v145, v146
	v_cvt_pk_bf16_f32 v69, v147, v148
	v_exp_f32_e32 v90, v90
	v_exp_f32_e32 v91, v91
	v_exp_f32_e32 v92, v92
	v_mfma_f32_32x32x16_bf16 v[34:49], v[74:77], v[66:69], v[34:49]
	ds_read_b128 v[74:77], v142 offset:32288
	v_exp_f32_e32 v93, v93
	v_exp_f32_e32 v94, v94
	v_exp_f32_e32 v95, v95
	v_exp_f32_e32 v96, v96
	v_exp_f32_e32 v97, v97
	v_add_f32_e32 v51, v51, v82
	v_add_f32_e32 v52, v52, v83
	s_waitcnt lgkmcnt(0)
	v_mfma_f32_32x32x16_bf16 v[18:33], v[74:77], v[66:69], v[18:33]
	ds_read_b128 v[74:77], v142 offset:27712
	v_add_f32_e32 v51, v51, v84
	v_add_f32_e32 v52, v52, v85
	v_add_f32_e32 v51, v51, v86
	v_add_f32_e32 v52, v52, v87
	v_cvt_pk_bf16_f32 v66, v82, v83
	v_cvt_pk_bf16_f32 v67, v84, v85
	v_cvt_pk_bf16_f32 v68, v86, v87
	v_cvt_pk_bf16_f32 v69, v88, v89
	s_waitcnt lgkmcnt(0)
	s_nop 0
	v_mfma_f32_32x32x16_bf16 v[34:49], v[74:77], v[66:69], v[34:49]
	ds_read_b128 v[74:77], v142 offset:32320
	v_add_f32_e32 v51, v51, v88
	v_add_f32_e32 v52, v52, v89
	v_add_f32_e32 v51, v51, v90
	v_add_f32_e32 v52, v52, v91
	s_waitcnt lgkmcnt(0)
	v_mfma_f32_32x32x16_bf16 v[18:33], v[74:77], v[66:69], v[18:33]
	v_cvt_pk_bf16_f32 v66, v90, v91
	v_cvt_pk_bf16_f32 v67, v92, v93
	v_cvt_pk_bf16_f32 v68, v94, v95
	v_cvt_pk_bf16_f32 v69, v96, v97
	ds_read_b128 v[74:77], v142 offset:27744
	ds_read_b128 v[70:73], v142 offset:32352
	v_add_f32_e32 v51, v51, v92
	v_add_f32_e32 v52, v52, v93
	v_add_f32_e32 v51, v51, v94
	v_add_f32_e32 v52, v52, v95
	v_add_f32_e32 v51, v51, v96
	v_add_f32_e32 v52, v52, v97
	s_waitcnt lgkmcnt(0)
	s_barrier
	v_mfma_f32_32x32x16_bf16 v[34:49], v[74:77], v[66:69], v[34:49]
	v_mfma_f32_32x32x16_bf16 v[18:33], v[70:73], v[66:69], v[18:33]
	s_cbranch_vccz .LBB0_267

; DI void attn_item(const Params& p, int layer, int item, char* smem) {
;     ...
;       f32x16 S[2];
; #pragma unroll
;       for (int kt = 0; kt < 2; ++kt) {
; #pragma unroll
;         for (int s = 0; s < 4; ++s) {
;           bf16x8 kf = *(const bf16x8*)(sK + (kt * 32 + l32) * KROW + s * 32 + h * 16);
;           S[kt] = MFMA32(kf, qf[s], s == 0 ? cinit : S[kt]);
;         }
;       }
;       if (tile < 64 && maskmode == 1) {
;         int qr = tq >> 6, qc = tq & 63;
;         int ws = min(max(qc - 8, 0), 48);
;         int dr = tile - qr + 7;
; #pragma unroll
;         for (int kt = 0; kt < 2; ++kt)
; #pragma unroll
;           for (int r = 0; r < 16; ++r) {
;             int kc = kt * 32 + crow(r, h);
;             bool ok = (unsigned)(kc - ws) < 16u;
;             int bi = ok ? (dr * 31 + kc - qc + 15) : 0;
;             float bv = s_rpb[bi];
;             S[kt][r] = ok ? (S[kt][r] + bv) : -INFINITY;
;           }
;       } else if (tile < 64 && maskmode == 2) {
; #pragma unroll
;         for (int kt = 0; kt < 2; ++kt)
; #pragma unroll
;           for (int r = 0; r < 16; ++r) {
;             int tk = tile * 64 + kt * 32 + crow(r, h);
;             int dd = tq - tk;
;             bool ok = (dd <= 128) && (dd >= -128);
;             S[kt][r] = ok ? S[kt][r] : -INFINITY;
;           }
;       }
; #pragma unroll
;       for (int r = 0; r < 16; ++r) {
;         S[0][r] = __builtin_amdgcn_exp2f(S[0][r]);
;         S[1][r] = __builtin_amdgcn_exp2f(S[1][r]);
;       }
; #pragma unroll
;       for (int kt = 0; kt < 2; ++kt)
; #pragma unroll
;         for (int s2 = 0; s2 < 2; ++s2) {
;           uint4 pw;
;           pw.x = pack_bf16(S[kt][8 * s2 + 0], S[kt][8 * s2 + 1]);
;           pw.y = pack_bf16(S[kt][8 * s2 + 2], S[kt][8 * s2 + 3]);
;           pw.z = pack_bf16(S[kt][8 * s2 + 4], S[kt][8 * s2 + 5]);
;           pw.w = pack_bf16(S[kt][8 * s2 + 6], S[kt][8 * s2 + 7]);
;           bf16x8 pf = __builtin_bit_cast(bf16x8, pw);
;           const int koff = (kt * 32 + 16 * s2 + 8 * h) * 2;
;           {
;             bf16x8 vf = *(const bf16x8*)(sV + l32 * VROW + koff);
;             o0 = MFMA32(vf, pf, o0);
;             lacc = MFMA32(ones, pf, lacc);
;           }
;           {
;             bf16x8 vf = *(const bf16x8*)(sV + (32 + l32) * VROW + koff);
;             o1 = MFMA32(vf, pf, o1);
;           }
;         }
.LBB0_263:
	ds_read_b128 v[82:85], v144
	ds_read_b128 v[86:89], v144 offset:32
	s_cmpk_gt_u32 s2, 0x41
	s_cselect_b64 s[0:1], -1, 0
	s_and_b64 vcc, exec, s[0:1]
	s_waitcnt lgkmcnt(1)
	v_mfma_f32_32x32x16_bf16 v[66:81], v[82:85], v[98:101], v[2:17]
	ds_read_b128 v[82:85], v144 offset:64
	ds_read_b128 v[146:149], v144 offset:4608
	s_waitcnt lgkmcnt(2)
	v_mfma_f32_32x32x16_bf16 v[66:81], v[86:89], v[102:105], v[66:81]
	s_waitcnt lgkmcnt(1)
	v_mfma_f32_32x32x16_bf16 v[66:81], v[82:85], v[106:109], v[66:81]
	ds_read_b128 v[82:85], v144 offset:96
	s_waitcnt lgkmcnt(0)
	v_mfma_f32_32x32x16_bf16 v[66:81], v[82:85], v[110:113], v[66:81]
	v_mfma_f32_32x32x16_bf16 v[82:97], v[146:149], v[98:101], v[2:17]
	ds_read_b128 v[146:149], v144 offset:4640
	s_nop 9
	v_exp_f32_e32 v66, v66
	v_exp_f32_e32 v67, v67
	v_exp_f32_e32 v68, v68
	v_exp_f32_e32 v69, v69
	v_exp_f32_e32 v70, v70
	v_exp_f32_e32 v71, v71
	s_waitcnt lgkmcnt(0)
	v_mfma_f32_32x32x16_bf16 v[82:97], v[146:149], v[102:105], v[82:97]
	ds_read_b128 v[146:149], v144 offset:4672
	v_exp_f32_e32 v72, v72
	v_exp_f32_e32 v73, v73
	v_exp_f32_e32 v145, v74
	v_add_f32_e32 v51, v51, v66
	v_add_f32_e32 v52, v52, v67
	v_add_f32_e32 v51, v51, v68
	v_add_f32_e32 v52, v52, v69
	v_cvt_pk_bf16_f32 v66, v66, v67
	v_cvt_pk_bf16_f32 v67, v68, v69
	s_waitcnt lgkmcnt(0)
	v_mfma_f32_32x32x16_bf16 v[82:97], v[146:149], v[106:109], v[82:97]
	ds_read_b128 v[146:149], v144 offset:4704
	v_add_f32_e32 v51, v51, v70
	v_add_f32_e32 v52, v52, v71
	v_cvt_pk_bf16_f32 v68, v70, v71
	v_add_f32_e32 v51, v51, v72
	v_add_f32_e32 v52, v52, v73
	v_cvt_pk_bf16_f32 v69, v72, v73
	v_exp_f32_e32 v150, v79
	v_exp_f32_e32 v151, v80
	s_waitcnt lgkmcnt(0)
	v_mfma_f32_32x32x16_bf16 v[82:97], v[146:149], v[110:113], v[82:97]
	v_exp_f32_e32 v152, v81
	v_exp_f32_e32 v146, v75
	v_exp_f32_e32 v147, v76
	v_exp_f32_e32 v148, v77
	v_exp_f32_e32 v149, v78
	ds_read_b128 v[70:73], v142 offset:9216
	ds_read_b128 v[74:77], v142 offset:9248
	ds_read_b128 v[78:81], v142 offset:13824
	v_add_f32_e32 v51, v51, v145
	v_add_f32_e32 v52, v52, v150
	v_add_f32_e32 v51, v51, v151
	v_add_f32_e32 v52, v52, v152
	v_exp_f32_e32 v82, v82
	s_waitcnt lgkmcnt(2)
	v_mfma_f32_32x32x16_bf16 v[34:49], v[70:73], v[66:69], v[34:49]
	v_exp_f32_e32 v83, v83
	v_exp_f32_e32 v84, v84
	v_exp_f32_e32 v85, v85
	v_add_f32_e32 v51, v51, v146
	v_add_f32_e32 v52, v52, v147
	v_add_f32_e32 v51, v51, v148
	v_add_f32_e32 v52, v52, v149
	v_exp_f32_e32 v86, v86
	v_exp_f32_e32 v87, v87
	v_exp_f32_e32 v88, v88
	v_exp_f32_e32 v89, v89
	s_waitcnt lgkmcnt(0)
	v_mfma_f32_32x32x16_bf16 v[18:33], v[78:81], v[66:69], v[18:33]
	v_cvt_pk_bf16_f32 v66, v145, v146
	v_cvt_pk_bf16_f32 v67, v147, v148
	v_cvt_pk_bf16_f32 v68, v149, v150
	v_cvt_pk_bf16_f32 v69, v151, v152
	v_exp_f32_e32 v90, v90
	v_exp_f32_e32 v91, v91
	v_exp_f32_e32 v92, v92
	v_mfma_f32_32x32x16_bf16 v[34:49], v[74:77], v[66:69], v[34:49]
	ds_read_b128 v[74:77], v142 offset:13856
	v_exp_f32_e32 v93, v93
	v_exp_f32_e32 v94, v94
	v_exp_f32_e32 v95, v95
	v_exp_f32_e32 v96, v96
	v_exp_f32_e32 v97, v97
	v_add_f32_e32 v51, v51, v82
	v_add_f32_e32 v52, v52, v83
	s_waitcnt lgkmcnt(0)
	v_mfma_f32_32x32x16_bf16 v[18:33], v[74:77], v[66:69], v[18:33]
	ds_read_b128 v[74:77], v142 offset:9280
	v_add_f32_e32 v51, v51, v84
	v_add_f32_e32 v52, v52, v85
	v_add_f32_e32 v51, v51, v86
	v_add_f32_e32 v52, v52, v87
	v_cvt_pk_bf16_f32 v66, v82, v83
	v_cvt_pk_bf16_f32 v67, v84, v85
	v_cvt_pk_bf16_f32 v68, v86, v87
	v_cvt_pk_bf16_f32 v69, v88, v89
	s_waitcnt lgkmcnt(0)
	s_nop 0
	v_mfma_f32_32x32x16_bf16 v[34:49], v[74:77], v[66:69], v[34:49]
	ds_read_b128 v[74:77], v142 offset:13888
	v_add_f32_e32 v51, v51, v88
	v_add_f32_e32 v52, v52, v89
	v_add_f32_e32 v51, v51, v90
	v_add_f32_e32 v52, v52, v91
	s_waitcnt lgkmcnt(0)
	v_mfma_f32_32x32x16_bf16 v[18:33], v[74:77], v[66:69], v[18:33]
	v_cvt_pk_bf16_f32 v66, v90, v91
	v_cvt_pk_bf16_f32 v67, v92, v93
	v_cvt_pk_bf16_f32 v68, v94, v95
	v_cvt_pk_bf16_f32 v69, v96, v97
	ds_read_b128 v[74:77], v142 offset:9312
	ds_read_b128 v[70:73], v142 offset:13920
	v_add_f32_e32 v51, v51, v92
	v_add_f32_e32 v52, v52, v93
	v_add_f32_e32 v51, v51, v94
	v_add_f32_e32 v52, v52, v95
	v_add_f32_e32 v51, v51, v96
	v_add_f32_e32 v52, v52, v97
	s_waitcnt lgkmcnt(0)
	s_barrier
	v_mfma_f32_32x32x16_bf16 v[34:49], v[74:77], v[66:69], v[34:49]
	v_mfma_f32_32x32x16_bf16 v[18:33], v[70:73], v[66:69], v[18:33]
	s_cbranch_vccnz .LBB0_265
	s_waitcnt vmcnt(1)
	ds_write_b128 v135, v[122:125]
	s_waitcnt vmcnt(0)
	ds_write2_b64 v141, v[126:127], v[128:129] offset0:128 offset1:130

; DI void attn_item(const Params& p, int layer, int item, char* smem) {
;     ...
;   float l_tot = lacc[0];
;   if (hasSink) l_tot += __builtin_amdgcn_exp2f(sinkv * LOG2E - m_fix);
;   float inv = 1.f / l_tot;
;   int T = (mode == 3) ? (TLAT + b * 256 + (qpos - 4096)) : (b * 4096 + qpos);
;   u16* od = p.O + (size_t)T * LDK + head16 * 64;
; #pragma unroll
;   for (int g = 0; g < 4; ++g) {
;     int d0 = 8 * g + 4 * h;
;     *(uint2*)(od + d0) = make_uint2(pack_bf16(o0[4 * g] * inv, o0[4 * g + 1] * inv), pack_bf16(o0[4 * g + 2] * inv, o0[4 * g + 3] * inv));
;     *(uint2*)(od + 32 + d0) = make_uint2(pack_bf16(o1[4 * g] * inv, o1[4 * g + 1] * inv), pack_bf16(o1[4 * g + 2] * inv, o1[4 * g + 3] * inv));
;   }
.LBB0_267:
	s_nop 5
	v_add_f32_e32 v51, v51, v52
	s_nop 0
	v_mov_b32_e32 v52, v51
	s_nop 1
	v_permlane32_swap_b32_e32 v51, v52
	s_nop 1
	v_add_f32_e32 v50, v50, v51
	v_add_f32_e32 v50, v50, v52
	v_div_scale_f32 v0, s[0:1], v50, v50, 1.0
	v_rcp_f32_e32 v3, v0
	v_lshl_add_u32 v2, s5, 12, v134
	s_lshl_b32 s0, s4, 6
	s_ashr_i32 s1, s0, 31
	v_fma_f32 v4, -v0, v3, 1.0
	v_fmac_f32_e32 v3, v4, v3
	v_div_scale_f32 v4, vcc, 1.0, v50, 1.0
	v_mul_f32_e32 v5, v4, v3
	v_fma_f32 v6, -v0, v5, v4
	v_fmac_f32_e32 v5, v6, v3
	v_fma_f32 v0, -v0, v5, v4
	v_div_fmas_f32 v0, v0, v3, v5
	v_ashrrev_i32_e32 v3, 31, v2
	v_lshlrev_b64 v[2:3], 11, v[2:3]
	v_div_fixup_f32 v4, v0, v50, 1.0
	v_lshl_add_u64 v[2:3], s[90:91], 0, v[2:3]
	v_lshl_add_u64 v[2:3], s[0:1], 1, v[2:3]
	v_pk_mul_f32 v[6:7], v[34:35], v[4:5] op_sel_hi:[1,0]
	v_pk_mul_f32 v[8:9], v[36:37], v[4:5] op_sel_hi:[1,0]
	v_lshlrev_b32_e32 v0, 3, v140
	v_cvt_pk_bf16_f32 v6, v6, v7
	v_cvt_pk_bf16_f32 v7, v8, v9
	v_lshl_add_u64 v[2:3], v[2:3], 0, v[0:1]
	global_store_dwordx2 v[2:3], v[6:7], off offset:1280
	v_pk_mul_f32 v[6:7], v[4:5], v[18:19] op_sel_hi:[0,1]
	v_pk_mul_f32 v[8:9], v[4:5], v[20:21] op_sel_hi:[0,1]
	v_cvt_pk_bf16_f32 v6, v6, v7
	v_cvt_pk_bf16_f32 v7, v8, v9
	global_store_dwordx2 v[2:3], v[6:7], off offset:1344
	v_pk_mul_f32 v[6:7], v[38:39], v[4:5] op_sel_hi:[1,0]
	v_pk_mul_f32 v[8:9], v[40:41], v[4:5] op_sel_hi:[1,0]
	v_cvt_pk_bf16_f32 v6, v6, v7
	v_cvt_pk_bf16_f32 v7, v8, v9
	global_store_dwordx2 v[2:3], v[6:7], off offset:1296
	v_pk_mul_f32 v[6:7], v[4:5], v[22:23] op_sel_hi:[0,1]
	v_pk_mul_f32 v[8:9], v[4:5], v[24:25] op_sel_hi:[0,1]
	v_cvt_pk_bf16_f32 v6, v6, v7
	v_cvt_pk_bf16_f32 v7, v8, v9
	global_store_dwordx2 v[2:3], v[6:7], off offset:1360
	v_pk_mul_f32 v[6:7], v[42:43], v[4:5] op_sel_hi:[1,0]
	v_pk_mul_f32 v[8:9], v[44:45], v[4:5] op_sel_hi:[1,0]
	v_cvt_pk_bf16_f32 v6, v6, v7
	v_cvt_pk_bf16_f32 v7, v8, v9
	global_store_dwordx2 v[2:3], v[6:7], off offset:1312
	v_pk_mul_f32 v[6:7], v[4:5], v[26:27] op_sel_hi:[0,1]
	v_pk_mul_f32 v[8:9], v[4:5], v[28:29] op_sel_hi:[0,1]
	v_cvt_pk_bf16_f32 v6, v6, v7
	v_cvt_pk_bf16_f32 v7, v8, v9
	global_store_dwordx2 v[2:3], v[6:7], off offset:1376
	v_pk_mul_f32 v[6:7], v[46:47], v[4:5] op_sel_hi:[1,0]
	v_pk_mul_f32 v[8:9], v[48:49], v[4:5] op_sel_hi:[1,0]
	v_cvt_pk_bf16_f32 v6, v6, v7
	v_cvt_pk_bf16_f32 v7, v8, v9
	global_store_dwordx2 v[2:3], v[6:7], off offset:1328
	v_pk_mul_f32 v[6:7], v[4:5], v[30:31] op_sel_hi:[0,1]
	v_pk_mul_f32 v[4:5], v[4:5], v[32:33] op_sel_hi:[0,1]
	v_cvt_pk_bf16_f32 v6, v6, v7
	v_cvt_pk_bf16_f32 v7, v4, v5
	global_store_dwordx2 v[2:3], v[6:7], off offset:1392
	s_and_saveexec_b64 s[0:1], s[68:69]
	s_cbranch_execz .LBB0_236
	s_branch .LBB0_498
